# in-attention half of the HM head-norm streaming moved from items 0-1 to items 2-3 of each workgroup
# baseline (speedup 1.0000x reference)
; __device__ __forceinline__ void p5_fixup(const Params& p) {
;     ...
;         for (int u = 0; u < 4; ++u) { const int v = v0 + u * gsz; if (v < T_TOK * 128) { const int row = v >> 7, head = (v >> 5) & 3;
;             hv[u] = __builtin_nontemporal_load((const u32x4*)(HM + (size_t)v * 8)); s0[u] = *(const float4*)(SSQ + ((size_t)row * 4 + head) * 8); s1[u] = *(const float4*)(SSQ + ((size_t)row * 4 + head) * 8 + 4); } }
.Lat_norope:
	s_or_b64 exec, exec, s[0:1]
	s_cmp_lt_u32 s98, 2
	s_cbranch_scc1 .Lhm_noissue
	s_cmp_gt_u32 s98, 3
	s_cbranch_scc1 .Lhm_noissue
	v_mov_b32_e32 v252, s98
	v_lshl_add_u32 v255, v252, 23, v250
	v_lshl_add_u32 v252, v252, 19, v251
	global_load_dwordx4 v[230:233], v255, s[100:101] nt
	v_add_u32_e32 v255, 0x2000, v255
	global_load_dwordx4 v[234:237], v255, s[100:101] nt
	v_add_u32_e32 v255, 0x2000, v255
	global_load_dwordx4 v[238:241], v255, s[100:101] nt
	v_add_u32_e32 v255, 0x2000, v255
	global_load_dwordx4 v[242:245], v255, s[100:101] nt
	global_load_dword v246, v252, s[88:89]
	global_load_dword v247, v252, s[88:89] offset:512
	global_load_dword v248, v252, s[88:89] offset:1024
	global_load_dword v249, v252, s[88:89] offset:1536
	s_waitcnt vmcnt(8)
	s_branch .Lhm_issued

; __device__ __forceinline__ void st_wt16(void* p, u32x4 v) { asm volatile("global_store_dwordx4 %0, %1, off sc1\n\ts_nop 1" : : "v"(p), "v"(v) : "memory"); }
; __device__ __forceinline__ void p5_fixup(const Params& p) {
;     ...
;         for (int u = 0; u < 4; ++u) { const int v = v0 + u * gsz; if (v < T_TOK * 128) {
;             const float ss = (s0[u].x + s0[u].y) + (s0[u].z + s0[u].w) + (s1[u].x + s1[u].y) + (s1[u].z + s1[u].w);
;             const float rstd = rsqrtf(ss * (1.0f / 256.0f) + EPS);
;             float f[8]; unpack8(hv[u], f);
; #pragma unroll
;             for (int e = 0; e < 8; ++e) f[e] *= rstd;
;             st_wt16(HM + (size_t)v * 8, pack8(f)); } }
.Lattn_pf_done:
	s_cmp_lt_u32 s98, 2
	s_cbranch_scc1 .Lhm_noconsume
	s_cmp_gt_u32 s98, 3
	s_cbranch_scc1 .Lhm_noconsume
	v_add_f32_dpp v246, v246, v246 quad_perm:[1,0,3,2] row_mask:0xf bank_mask:0xf
	v_add_f32_dpp v247, v247, v247 quad_perm:[1,0,3,2] row_mask:0xf bank_mask:0xf
	v_add_f32_dpp v248, v248, v248 quad_perm:[1,0,3,2] row_mask:0xf bank_mask:0xf
	v_add_f32_dpp v249, v249, v249 quad_perm:[1,0,3,2] row_mask:0xf bank_mask:0xf
	v_add_f32_dpp v246, v246, v246 quad_perm:[2,3,0,1] row_mask:0xf bank_mask:0xf
	v_add_f32_dpp v247, v247, v247 quad_perm:[2,3,0,1] row_mask:0xf bank_mask:0xf
	v_add_f32_dpp v248, v248, v248 quad_perm:[2,3,0,1] row_mask:0xf bank_mask:0xf
	v_add_f32_dpp v249, v249, v249 quad_perm:[2,3,0,1] row_mask:0xf bank_mask:0xf
	v_add_f32_dpp v246, v246, v246 row_half_mirror row_mask:0xf bank_mask:0xf
	v_add_f32_dpp v247, v247, v247 row_half_mirror row_mask:0xf bank_mask:0xf
	v_add_f32_dpp v248, v248, v248 row_half_mirror row_mask:0xf bank_mask:0xf
	v_add_f32_dpp v249, v249, v249 row_half_mirror row_mask:0xf bank_mask:0xf
	v_mov_b32_e32 v252, 0x358637bd
	v_mov_b32_e32 v255, s98
	v_fmamk_f32 v246, v246, 0x3b800000, v252
	v_fmamk_f32 v247, v247, 0x3b800000, v252
	v_fmamk_f32 v248, v248, 0x3b800000, v252
	v_fmamk_f32 v249, v249, 0x3b800000, v252
	v_rsq_f32_e32 v246, v246
	v_rsq_f32_e32 v247, v247
	v_rsq_f32_e32 v248, v248
	v_rsq_f32_e32 v249, v249
	v_lshl_add_u32 v255, v255, 23, v250
	v_lshlrev_b32_e32 v252, 16, v230
	v_and_b32_e32 v253, 0xffff0000, v230
	v_mul_f32_e32 v252, v246, v252
	v_mul_f32_e32 v253, v246, v253
	v_cvt_pk_bf16_f32 v230, v252, v253
	v_lshlrev_b32_e32 v252, 16, v231
	v_and_b32_e32 v253, 0xffff0000, v231
	v_mul_f32_e32 v252, v246, v252
	v_mul_f32_e32 v253, v246, v253
	v_cvt_pk_bf16_f32 v231, v252, v253
	v_lshlrev_b32_e32 v252, 16, v232
	v_and_b32_e32 v253, 0xffff0000, v232
	v_mul_f32_e32 v252, v246, v252
	v_mul_f32_e32 v253, v246, v253
	v_cvt_pk_bf16_f32 v232, v252, v253
	v_lshlrev_b32_e32 v252, 16, v233
	v_and_b32_e32 v253, 0xffff0000, v233
	v_mul_f32_e32 v252, v246, v252
	v_mul_f32_e32 v253, v246, v253
	v_cvt_pk_bf16_f32 v233, v252, v253
	global_store_dwordx4 v255, v[230:233], s[100:101]
	v_add_u32_e32 v255, 0x2000, v255
	v_lshlrev_b32_e32 v252, 16, v234
	v_and_b32_e32 v253, 0xffff0000, v234
	v_mul_f32_e32 v252, v247, v252
	v_mul_f32_e32 v253, v247, v253
	v_cvt_pk_bf16_f32 v234, v252, v253
	v_lshlrev_b32_e32 v252, 16, v235
	v_and_b32_e32 v253, 0xffff0000, v235
	v_mul_f32_e32 v252, v247, v252
	v_mul_f32_e32 v253, v247, v253
	v_cvt_pk_bf16_f32 v235, v252, v253
	v_lshlrev_b32_e32 v252, 16, v236
	v_and_b32_e32 v253, 0xffff0000, v236
	v_mul_f32_e32 v252, v247, v252
	v_mul_f32_e32 v253, v247, v253
	v_cvt_pk_bf16_f32 v236, v252, v253
	v_lshlrev_b32_e32 v252, 16, v237
	v_and_b32_e32 v253, 0xffff0000, v237
	v_mul_f32_e32 v252, v247, v252
	v_mul_f32_e32 v253, v247, v253
	v_cvt_pk_bf16_f32 v237, v252, v253
	global_store_dwordx4 v255, v[234:237], s[100:101]
	v_add_u32_e32 v255, 0x2000, v255
	v_lshlrev_b32_e32 v252, 16, v238
	v_and_b32_e32 v253, 0xffff0000, v238
	v_mul_f32_e32 v252, v248, v252
	v_mul_f32_e32 v253, v248, v253
	v_cvt_pk_bf16_f32 v238, v252, v253
	v_lshlrev_b32_e32 v252, 16, v239
	v_and_b32_e32 v253, 0xffff0000, v239
	v_mul_f32_e32 v252, v248, v252
	v_mul_f32_e32 v253, v248, v253
	v_cvt_pk_bf16_f32 v239, v252, v253
	v_lshlrev_b32_e32 v252, 16, v240
	v_and_b32_e32 v253, 0xffff0000, v240
	v_mul_f32_e32 v252, v248, v252
	v_mul_f32_e32 v253, v248, v253
	v_cvt_pk_bf16_f32 v240, v252, v253
	v_lshlrev_b32_e32 v252, 16, v241
	v_and_b32_e32 v253, 0xffff0000, v241
	v_mul_f32_e32 v252, v248, v252
	v_mul_f32_e32 v253, v248, v253
	v_cvt_pk_bf16_f32 v241, v252, v253
	global_store_dwordx4 v255, v[238:241], s[100:101]
	v_add_u32_e32 v255, 0x2000, v255
	v_lshlrev_b32_e32 v252, 16, v242
	v_and_b32_e32 v253, 0xffff0000, v242
	v_mul_f32_e32 v252, v249, v252
	v_mul_f32_e32 v253, v249, v253
	v_cvt_pk_bf16_f32 v242, v252, v253
	v_lshlrev_b32_e32 v252, 16, v243
	v_and_b32_e32 v253, 0xffff0000, v243
	v_mul_f32_e32 v252, v249, v252
	v_mul_f32_e32 v253, v249, v253
	v_cvt_pk_bf16_f32 v243, v252, v253
	v_lshlrev_b32_e32 v252, 16, v244
	v_and_b32_e32 v253, 0xffff0000, v244
	v_mul_f32_e32 v252, v249, v252
	v_mul_f32_e32 v253, v249, v253
	v_cvt_pk_bf16_f32 v244, v252, v253
	v_lshlrev_b32_e32 v252, 16, v245
	v_and_b32_e32 v253, 0xffff0000, v245
	v_mul_f32_e32 v252, v249, v252
	v_mul_f32_e32 v253, v249, v253
	v_cvt_pk_bf16_f32 v245, v252, v253
	global_store_dwordx4 v255, v[242:245], s[100:101]
	s_nop 1
